# GEMM1+GEMM2 k-loops: LDS ring 3->4 stages, LDS-DMA issued 3 k-steps ahead
# speedup vs baseline: 1.0118x; 1.0050x over previous
.LBB0_688:
	s_ashr_i32 s0, s19, 31
	s_lshr_b32 s0, s0, 30
	s_add_i32 s0, s19, s0
	s_and_b32 s1, s0, 0x1ffffc
	s_lshl_b32 s0, s0, 8
	s_lshl_b32 s2, s27, 8
	s_sub_i32 s1, s19, s1
	s_and_b32 s0, s0, 0xfffffc00
	s_and_b32 s2, s2, 0x300
	s_or_b32 s14, s2, s0
	s_lshl_b32 s0, s1, 11
	s_lshl_b32 s1, s27, 6
	s_and_b32 s1, s1, 0xffffff00
	s_add_i32 s15, s1, s0
	s_add_i32 s0, s27, s26
	s_add_i32 s1, s19, 8
	s_cmp_gt_i32 s0, 31
	s_cselect_b32 s27, s25, s0
	s_cselect_b32 s19, s1, s19
	s_cmpk_lt_u32 s15, 0x800
	s_cselect_b64 s[0:1], -1, 0
	s_and_b32 s2, s15, 0xfffff800
	s_cmpk_eq_i32 s2, 0x1800
	s_cselect_b64 s[2:3], -1, 0
	s_or_b64 s[0:1], s[0:1], s[2:3]
	s_mul_hi_i32 s2, s14, 0x78787879
	s_lshr_b32 s3, s2, 31
	s_ashr_i32 s2, s2, 11
	s_add_i32 s2, s2, s3
	s_mulk_i32 s2, 0x1100
	s_sub_i32 s2, s14, s2
	s_cmpk_lt_i32 s2, 0x100
	s_cselect_b64 s[2:3], -1, 0
	s_and_b64 s[0:1], s[0:1], s[2:3]
	s_cmpk_lt_i32 s19, 0x44
	s_cselect_b64 s[2:3], -1, 0
	s_and_b64 s[2:3], s[0:1], s[2:3]
	s_and_b64 vcc, exec, s[2:3]
	s_cbranch_vccnz .LBB0_688
	v_bfe_u32 v4, v2, 4, 2
	v_sub_u32_e32 v0, 0, v4
	s_xor_b64 s[2:3], s[0:1], -1
	v_xor_b32_e32 v0, v2, v0
	s_waitcnt vmcnt(0)
	s_ashr_i32 s8, s4, 6
	v_cndmask_b32_e64 v1, 0, 1, s[2:3]
	v_and_b32_e32 v0, 3, v0
	s_mul_i32 s52, s24, 0x2200000
	v_bfe_u32 v3, v2, 2, 4
	s_lshl_b32 s5, s8, 4
	v_cmp_ne_u32_e64 s[0:1], 1, v1
	s_andn2_b64 vcc, exec, s[2:3]
	v_lshlrev_b32_e32 v0, 4, v0
	s_barrier
	s_cbranch_vccnz .LBB0_691
	v_or_b32_e32 v5, s5, v3
	v_add_u32_e32 v6, s14, v5
	s_add_u32 s2, s86, s52
	v_ashrrev_i32_e32 v7, 31, v6
	s_addc_u32 s3, s87, 0
	v_lshlrev_b64 v[6:7], 11, v[6:7]
	v_add_u32_e32 v8, s15, v5
	v_lshl_add_u64 v[6:7], s[2:3], 0, v[6:7]
	v_ashrrev_i32_e32 v9, 31, v8
	v_readlane_b32 s2, v253, 34
	v_lshlrev_b64 v[8:9], 11, v[8:9]
	v_readlane_b32 s3, v253, 35
	v_mov_b32_e32 v1, v176
	v_lshl_add_u64 v[6:7], v[6:7], 0, v[0:1]
	v_lshl_add_u64 v[8:9], s[2:3], 0, v[8:9]
	s_lshl_b32 s2, s8, 10
	s_mov_b32 m0, s2
	v_lshl_add_u64 v[8:9], v[8:9], 0, v[0:1]
	global_load_lds_dwordx4 v[6:7], off
	s_add_i32 m0, s2, 0x4000
	v_lshl_add_u64 v[10:11], v[6:7], 0, s[72:73]
	global_load_lds_dwordx4 v[8:9], off
	s_add_i32 m0, s2, 0x2000
	v_lshl_add_u64 v[12:13], v[8:9], 0, 64
	global_load_lds_dwordx4 v[10:11], off
	v_lshl_add_u64 v[10:11], v[8:9], 0, s[72:73]
	s_add_i32 m0, s2, 0x6000
	s_mov_b64 s[12:13], 0x40040
	global_load_lds_dwordx4 v[10:11], off
	v_lshl_add_u64 v[10:11], v[6:7], 0, 64
	s_add_i32 m0, s2, 0x8000
	v_lshl_add_u64 v[6:7], v[6:7], 0, s[12:13]
	global_load_lds_dwordx4 v[10:11], off
	s_add_i32 m0, s2, 0x10000
	v_lshl_add_u64 v[14:15], v[10:11], 0, 64
	global_load_lds_dwordx4 v[14:15], off
	s_add_i32 m0, s2, 0xc000
	s_nop 0
	global_load_lds_dwordx4 v[12:13], off
	s_add_i32 m0, s2, 0x14000
	v_lshl_add_u64 v[14:15], v[12:13], 0, 64
	global_load_lds_dwordx4 v[14:15], off
	s_add_i32 m0, s2, 0xa000
	s_nop 0
	global_load_lds_dwordx4 v[6:7], off
	s_add_i32 m0, s2, 0x12000
	v_lshl_add_u64 v[14:15], v[6:7], 0, 64
	global_load_lds_dwordx4 v[14:15], off
	v_lshl_add_u64 v[6:7], v[8:9], 0, s[12:13]
	s_add_i32 m0, s2, 0x16000
	v_lshl_add_u64 v[14:15], v[6:7], 0, 64
	global_load_lds_dwordx4 v[14:15], off
	s_add_i32 m0, s2, 0xe000
	s_nop 0
	global_load_lds_dwordx4 v[6:7], off
	s_waitcnt vmcnt(4)

.LBB0_693:
	s_and_b64 vcc, exec, s[0:1]
	s_cbranch_vccnz .LBB0_1057
	v_lshrrev_b32_e32 v1, 2, v2
	v_sub_u32_e32 v1, 0, v1
	s_bfe_u32 s0, s4, 0x20006
	v_bitop3_b32 v1, v4, v1, 3 bitop3:0x78
	s_ashr_i32 s1, s4, 8
	v_lshlrev_b32_e32 v202, 4, v1
	s_lshl_b32 s33, s1, 13
	s_lshl_b32 s34, s0, 12
	s_lshl_b32 s37, s1, 7
	s_lshl_b32 s40, s0, 6
	v_mov_b32_e32 v1, v176
	v_readlane_b32 s0, v252, 31
	v_lshlrev_b32_e32 v204, 2, v4
	v_lshl_add_u64 v[4:5], s[52:53], 0, v[0:1]
	v_readlane_b32 s1, v252, 32
	v_and_b32_e32 v177, 15, v2
	v_and_b32_e32 v205, 8, v204
	v_lshl_add_u64 v[178:179], s[0:1], 0, v[4:5]
	v_readlane_b32 s0, v252, 44
	v_readlane_b32 s1, v252, 45
	s_mov_b32 s38, 0
	v_lshlrev_b32_e32 v203, 6, v177
	v_lshl_add_u64 v[180:181], s[0:1], 0, v[0:1]
	v_readlane_b32 s0, v252, 33
	v_readlane_b32 s1, v252, 34
	s_lshl_b32 s35, s8, 10
	s_lshl_b32 s36, s8, 12
	v_lshl_add_u64 v[182:183], s[0:1], 0, v[4:5]
	v_readlane_b32 s0, v252, 48
	v_readlane_b32 s1, v252, 49
	v_and_or_b32 v206, v2, 16, v205
	v_and_b32_e32 v207, 31, v2
	v_add_u32_e32 v208, s5, v3
	v_lshl_add_u64 v[184:185], s[0:1], 0, v[0:1]
	v_cndmask_b32_e64 v209, 0, 1, s[2:3]
	s_mov_b32 s82, 0
	s_mov_b32 s52, 0
	v_lshl_add_u64 v[178:179], v[178:179], 0, 64
	v_lshl_add_u64 v[180:181], v[180:181], 0, 64
	v_lshl_add_u64 v[182:183], v[182:183], 0, 64
	v_lshl_add_u64 v[184:185], v[184:185], 0, 64
	s_branch .LBB0_696

.LBB0_701:
	s_add_i32 s2, s64, 1
	s_cmp_lg_u32 s64, 3
	s_waitcnt lgkmcnt(0)
	v_mfma_f32_16x16x32_bf16 v[124:127], v[148:151], v[172:175], v[124:127]
	s_cselect_b32 s64, s2, 0
	s_add_i32 s39, s39, 1
	s_waitcnt lgkmcnt(0)
	v_mfma_f32_16x16x32_bf16 v[120:123], v[144:147], v[172:175], v[120:123]
	s_add_u32 s8, s8, 64
	s_addc_u32 s9, s9, 0
	s_cmpk_eq_i32 s8, 0x800
	v_mfma_f32_16x16x32_bf16 v[116:119], v[136:139], v[172:175], v[116:119]
	s_barrier
	v_mfma_f32_16x16x32_bf16 v[112:115], v[132:135], v[172:175], v[112:115]
	v_mfma_f32_16x16x32_bf16 v[108:111], v[148:151], v[168:171], v[108:111]
	v_mfma_f32_16x16x32_bf16 v[104:107], v[144:147], v[168:171], v[104:107]
	v_mfma_f32_16x16x32_bf16 v[100:103], v[136:139], v[168:171], v[100:103]
	v_mfma_f32_16x16x32_bf16 v[96:99], v[132:135], v[168:171], v[96:99]
	v_mfma_f32_16x16x32_bf16 v[92:95], v[148:151], v[164:167], v[92:95]
	v_mfma_f32_16x16x32_bf16 v[88:91], v[144:147], v[164:167], v[88:91]
	v_mfma_f32_16x16x32_bf16 v[84:87], v[136:139], v[164:167], v[84:87]
	v_mfma_f32_16x16x32_bf16 v[80:83], v[132:135], v[164:167], v[80:83]
	v_mfma_f32_16x16x32_bf16 v[76:79], v[148:151], v[160:163], v[76:79]
	v_mfma_f32_16x16x32_bf16 v[72:75], v[144:147], v[160:163], v[72:75]
	v_mfma_f32_16x16x32_bf16 v[68:71], v[136:139], v[160:163], v[68:71]
	v_mfma_f32_16x16x32_bf16 v[64:67], v[132:135], v[160:163], v[64:67]
	v_mfma_f32_16x16x32_bf16 v[60:63], v[148:151], v[156:159], v[60:63]
	v_mfma_f32_16x16x32_bf16 v[56:59], v[144:147], v[156:159], v[56:59]
	v_mfma_f32_16x16x32_bf16 v[52:55], v[136:139], v[156:159], v[52:55]
	v_mfma_f32_16x16x32_bf16 v[48:51], v[132:135], v[156:159], v[48:51]
	v_mfma_f32_16x16x32_bf16 v[44:47], v[148:151], v[152:155], v[44:47]
	v_mfma_f32_16x16x32_bf16 v[40:43], v[144:147], v[152:155], v[40:43]
	v_mfma_f32_16x16x32_bf16 v[36:39], v[136:139], v[152:155], v[36:39]
	v_mfma_f32_16x16x32_bf16 v[32:35], v[132:135], v[152:155], v[32:35]
	v_mfma_f32_16x16x32_bf16 v[28:31], v[148:151], v[140:143], v[28:31]
	v_mfma_f32_16x16x32_bf16 v[24:27], v[144:147], v[140:143], v[24:27]
	v_mfma_f32_16x16x32_bf16 v[20:23], v[136:139], v[140:143], v[20:23]
	v_mfma_f32_16x16x32_bf16 v[16:19], v[132:135], v[140:143], v[16:19]
	v_mfma_f32_16x16x32_bf16 v[12:15], v[148:151], v[128:131], v[12:15]
	v_mfma_f32_16x16x32_bf16 v[8:11], v[144:147], v[128:131], v[8:11]
	v_mfma_f32_16x16x32_bf16 v[4:7], v[136:139], v[128:131], v[4:7]
	v_mfma_f32_16x16x32_bf16 v[0:3], v[132:135], v[128:131], v[0:3]
	s_cbranch_scc1 .LBB0_706
.LBB0_702:
	s_lshl_b32 s54, s64, 15
	v_or_b32_e32 v132, s54, v202
	v_add3_u32 v128, v132, s33, v203
	s_barrier
	ds_read_b128 v[172:175], v128
	ds_read_b128 v[168:171], v128 offset:1024
	ds_read_b128 v[164:167], v128 offset:2048
	ds_read_b128 v[160:163], v128 offset:3072
	ds_read_b128 v[156:159], v128 offset:4096
	ds_read_b128 v[152:155], v128 offset:5120
	ds_read_b128 v[140:143], v128 offset:6144
	ds_read_b128 v[128:131], v128 offset:7168
	v_add3_u32 v132, v132, s34, v203
	ds_read_b128 v[148:151], v132 offset:16384
	ds_read_b128 v[144:147], v132 offset:17408
	ds_read_b128 v[136:139], v132 offset:18432
	ds_read_b128 v[132:135], v132 offset:19456
	s_cmp_lt_u32 s39, 29
	s_cselect_b64 s[2:3], -1, 0
	s_or_b64 s[12:13], s[16:17], s[2:3]
	s_cbranch_scc1 .Lgk_i3
	s_waitcnt vmcnt(0)
	s_branch .LBB0_701
.Lgk_i3:
	v_lshl_add_u64 v[194:195], v[192:193], 0, s[8:9]
	v_lshl_add_u64 v[196:197], v[188:189], 0, s[8:9]
	s_addk_i32 s54, 0x8000
	v_cndmask_b32_e64 v195, v197, v195, s[2:3]
	v_cndmask_b32_e64 v194, v196, v194, s[2:3]
	v_lshl_add_u64 v[196:197], v[190:191], 0, s[8:9]
	v_lshl_add_u64 v[198:199], v[186:187], 0, s[8:9]
	s_cmp_gt_i32 s64, 0
	v_cndmask_b32_e64 v197, v199, v197, s[2:3]
	v_cndmask_b32_e64 v196, v198, v196, s[2:3]
	s_cselect_b32 s2, s54, 0x18000
	s_add_i32 s2, s35, s2
	s_add_i32 s13, s2, 0x4000
	s_mov_b32 m0, s2
	s_add_i32 s12, s2, 0x2000
	global_load_lds_dwordx4 v[196:197], off
	s_mov_b32 m0, s13
	s_add_i32 s3, s2, 0x6000
	v_lshl_add_u64 v[200:201], v[196:197], 0, s[72:73]
	global_load_lds_dwordx4 v[194:195], off
	s_mov_b32 m0, s12
	v_lshl_add_u64 v[198:199], v[194:195], 0, s[72:73]
	global_load_lds_dwordx4 v[200:201], off
	s_mov_b32 m0, s3
	s_nop 0
	global_load_lds_dwordx4 v[198:199], off
	s_waitcnt vmcnt(8)
	s_branch .LBB0_701

.LBB0_709:
	s_add_i32 s2, s64, 1
	s_cmp_lg_u32 s64, 3
	s_cselect_b32 s64, s2, 0
	s_add_i32 s39, s39, 1
	s_add_u32 s8, s8, 64
	s_addc_u32 s9, s9, 0
	s_cmpk_eq_i32 s8, 0x800
	s_barrier
	s_cbranch_scc1 .LBB0_716
.LBB0_710:
	s_lshl_b32 s54, s64, 15
	v_or_b32_e32 v128, s54, v202
	v_add_u32_e32 v132, v128, v203
	ds_read_b128 v[172:175], v132
	ds_read_b128 v[168:171], v132 offset:1024
	ds_read_b128 v[164:167], v132 offset:2048
	ds_read_b128 v[160:163], v132 offset:3072
	ds_read_b128 v[156:159], v132 offset:4096
	ds_read_b128 v[152:155], v132 offset:5120
	ds_read_b128 v[136:139], v132 offset:6144
	ds_read_b128 v[128:131], v132 offset:7168
	v_add_u32_e32 v132, s36, v132
	ds_read_b128 v[144:147], v132 offset:16384
	ds_read_b128 v[148:151], v132 offset:17408
	ds_read_b128 v[140:143], v132 offset:18432
	ds_read_b128 v[132:135], v132 offset:19456
	s_cmp_lt_u32 s39, 29
	s_cselect_b64 s[2:3], -1, 0
	s_nor_b64 s[12:13], s[16:17], s[2:3]
	s_cbranch_scc1 .LBB0_712
	v_lshl_add_u64 v[194:195], v[192:193], 0, s[8:9]
	v_lshl_add_u64 v[196:197], v[188:189], 0, s[8:9]
	s_addk_i32 s54, 0x8000
	v_cndmask_b32_e64 v195, v197, v195, s[2:3]
	v_cndmask_b32_e64 v194, v196, v194, s[2:3]
	v_lshl_add_u64 v[196:197], v[190:191], 0, s[8:9]
	v_lshl_add_u64 v[198:199], v[186:187], 0, s[8:9]
	s_cmp_gt_i32 s64, 0
	v_cndmask_b32_e64 v197, v199, v197, s[2:3]
	v_cndmask_b32_e64 v196, v198, v196, s[2:3]
	s_cselect_b32 s2, s54, 0x18000
	s_add_i32 s2, s35, s2
	s_add_i32 s55, s2, 0x4000
	s_mov_b32 m0, s2
	s_add_i32 s54, s2, 0x2000
	global_load_lds_dwordx4 v[196:197], off
	s_mov_b32 m0, s55
	s_add_i32 s3, s2, 0x6000
	v_lshl_add_u64 v[200:201], v[196:197], 0, s[72:73]
	global_load_lds_dwordx4 v[194:195], off
	s_mov_b32 m0, s54
	v_lshl_add_u64 v[198:199], v[194:195], 0, s[72:73]
	global_load_lds_dwordx4 v[200:201], off
	s_mov_b32 m0, s3
	s_nop 0
	global_load_lds_dwordx4 v[198:199], off

.LBB0_720:
	s_add_i32 s0, s64, 1
	s_cmp_lg_u32 s64, 3
	s_waitcnt lgkmcnt(0)
	v_mfma_f32_16x16x32_bf16 v[124:127], v[172:175], v[148:151], v[124:127]
	s_cselect_b32 s64, s0, 0
	s_add_i32 s12, s12, 1
	s_waitcnt lgkmcnt(0)
	v_mfma_f32_16x16x32_bf16 v[120:123], v[172:175], v[144:147], v[120:123]
	s_add_u32 s2, s2, 64
	s_addc_u32 s3, s3, 0
	s_cmpk_eq_i32 s2, 0x800
	v_mfma_f32_16x16x32_bf16 v[116:119], v[172:175], v[136:139], v[116:119]
	s_barrier
	v_mfma_f32_16x16x32_bf16 v[112:115], v[172:175], v[132:135], v[112:115]
	v_mfma_f32_16x16x32_bf16 v[108:111], v[168:171], v[148:151], v[108:111]
	v_mfma_f32_16x16x32_bf16 v[104:107], v[168:171], v[144:147], v[104:107]
	v_mfma_f32_16x16x32_bf16 v[100:103], v[168:171], v[136:139], v[100:103]
	v_mfma_f32_16x16x32_bf16 v[96:99], v[168:171], v[132:135], v[96:99]
	v_mfma_f32_16x16x32_bf16 v[92:95], v[164:167], v[148:151], v[92:95]
	v_mfma_f32_16x16x32_bf16 v[88:91], v[164:167], v[144:147], v[88:91]
	v_mfma_f32_16x16x32_bf16 v[84:87], v[164:167], v[136:139], v[84:87]
	v_mfma_f32_16x16x32_bf16 v[80:83], v[164:167], v[132:135], v[80:83]
	v_mfma_f32_16x16x32_bf16 v[76:79], v[160:163], v[148:151], v[76:79]
	v_mfma_f32_16x16x32_bf16 v[72:75], v[160:163], v[144:147], v[72:75]
	v_mfma_f32_16x16x32_bf16 v[68:71], v[160:163], v[136:139], v[68:71]
	v_mfma_f32_16x16x32_bf16 v[64:67], v[160:163], v[132:135], v[64:67]
	v_mfma_f32_16x16x32_bf16 v[60:63], v[156:159], v[148:151], v[60:63]
	v_mfma_f32_16x16x32_bf16 v[56:59], v[156:159], v[144:147], v[56:59]
	v_mfma_f32_16x16x32_bf16 v[52:55], v[156:159], v[136:139], v[52:55]
	v_mfma_f32_16x16x32_bf16 v[48:51], v[156:159], v[132:135], v[48:51]
	v_mfma_f32_16x16x32_bf16 v[44:47], v[152:155], v[148:151], v[44:47]
	v_mfma_f32_16x16x32_bf16 v[40:43], v[152:155], v[144:147], v[40:43]
	v_mfma_f32_16x16x32_bf16 v[36:39], v[152:155], v[136:139], v[36:39]
	v_mfma_f32_16x16x32_bf16 v[32:35], v[152:155], v[132:135], v[32:35]
	v_mfma_f32_16x16x32_bf16 v[28:31], v[140:143], v[148:151], v[28:31]
	v_mfma_f32_16x16x32_bf16 v[24:27], v[140:143], v[144:147], v[24:27]
	v_mfma_f32_16x16x32_bf16 v[20:23], v[140:143], v[136:139], v[20:23]
	v_mfma_f32_16x16x32_bf16 v[16:19], v[140:143], v[132:135], v[16:19]
	v_mfma_f32_16x16x32_bf16 v[12:15], v[128:131], v[148:151], v[12:15]
	v_mfma_f32_16x16x32_bf16 v[8:11], v[128:131], v[144:147], v[8:11]
	v_mfma_f32_16x16x32_bf16 v[4:7], v[128:131], v[136:139], v[4:7]
	v_mfma_f32_16x16x32_bf16 v[0:3], v[128:131], v[132:135], v[0:3]
	s_cbranch_scc1 .LBB0_725
.LBB0_721:
	s_lshl_b32 s13, s64, 15
	v_or_b32_e32 v132, s13, v202
	v_add3_u32 v128, v132, s33, v203
	s_barrier
	ds_read_b128 v[172:175], v128
	ds_read_b128 v[168:171], v128 offset:1024
	ds_read_b128 v[164:167], v128 offset:2048
	ds_read_b128 v[160:163], v128 offset:3072
	ds_read_b128 v[156:159], v128 offset:4096
	ds_read_b128 v[152:155], v128 offset:5120
	ds_read_b128 v[140:143], v128 offset:6144
	ds_read_b128 v[128:131], v128 offset:7168
	v_add3_u32 v132, v132, s34, v203
	ds_read_b128 v[148:151], v132 offset:16384
	ds_read_b128 v[144:147], v132 offset:17408
	ds_read_b128 v[136:139], v132 offset:18432
	ds_read_b128 v[132:135], v132 offset:19456
	s_cmp_lt_u32 s12, 29
	s_cselect_b64 s[0:1], -1, 0
	s_or_b64 s[8:9], s[16:17], s[0:1]
	s_cbranch_scc1 .Lgk_i4
	s_waitcnt vmcnt(0)
	s_branch .LBB0_720
.Lgk_i4:
	v_lshl_add_u64 v[210:211], v[200:201], 0, s[2:3]
	v_lshl_add_u64 v[212:213], v[196:197], 0, s[2:3]
	s_addk_i32 s13, 0x8000
	v_cndmask_b32_e64 v211, v213, v211, s[0:1]
	v_cndmask_b32_e64 v210, v212, v210, s[0:1]
	v_lshl_add_u64 v[212:213], v[198:199], 0, s[2:3]
	v_lshl_add_u64 v[214:215], v[194:195], 0, s[2:3]
	s_cmp_gt_i32 s64, 0
	v_cndmask_b32_e64 v213, v215, v213, s[0:1]
	v_cndmask_b32_e64 v212, v214, v212, s[0:1]
	s_cselect_b32 s0, s13, 0x18000
	s_add_i32 s0, s35, s0
	s_add_i32 s9, s0, 0x4000
	s_mov_b32 m0, s0
	s_add_i32 s8, s0, 0x2000
	global_load_lds_dwordx4 v[212:213], off
	s_mov_b32 m0, s9
	s_add_i32 s1, s0, 0x6000
	v_lshl_add_u64 v[216:217], v[212:213], 0, s[72:73]
	global_load_lds_dwordx4 v[210:211], off
	s_mov_b32 m0, s8
	v_lshl_add_u64 v[214:215], v[210:211], 0, s[72:73]
	global_load_lds_dwordx4 v[216:217], off
	s_mov_b32 m0, s1
	s_nop 0
	global_load_lds_dwordx4 v[214:215], off
	s_waitcnt vmcnt(8)
	s_branch .LBB0_720

.LBB0_728:
	s_add_i32 s0, s38, 1
	s_cmp_lg_u32 s38, 3
	s_cselect_b32 s38, s0, 0
	s_add_i32 s12, s12, 1
	s_add_u32 s2, s2, 64
	s_addc_u32 s3, s3, 0
	s_cmpk_eq_i32 s2, 0x800
	s_barrier
	s_cbranch_scc1 .LBB0_735
.LBB0_729:
	s_lshl_b32 s13, s38, 15
	v_or_b32_e32 v128, s13, v202
	v_add_u32_e32 v132, v128, v203
	ds_read_b128 v[172:175], v132
	ds_read_b128 v[168:171], v132 offset:1024
	ds_read_b128 v[164:167], v132 offset:2048
	ds_read_b128 v[160:163], v132 offset:3072
	ds_read_b128 v[156:159], v132 offset:4096
	ds_read_b128 v[152:155], v132 offset:5120
	ds_read_b128 v[136:139], v132 offset:6144
	ds_read_b128 v[128:131], v132 offset:7168
	v_add_u32_e32 v132, s36, v132
	ds_read_b128 v[144:147], v132 offset:16384
	ds_read_b128 v[148:151], v132 offset:17408
	ds_read_b128 v[140:143], v132 offset:18432
	ds_read_b128 v[132:135], v132 offset:19456
	s_cmp_lt_u32 s12, 29
	s_cselect_b64 s[0:1], -1, 0
	s_nor_b64 s[8:9], s[16:17], s[0:1]
	s_cbranch_scc1 .LBB0_731
	v_lshl_add_u64 v[194:195], v[186:187], 0, s[2:3]
	v_lshl_add_u64 v[196:197], v[190:191], 0, s[2:3]
	s_addk_i32 s13, 0x8000
	v_cndmask_b32_e64 v195, v197, v195, s[0:1]
	v_cndmask_b32_e64 v194, v196, v194, s[0:1]
	v_lshl_add_u64 v[196:197], v[188:189], 0, s[2:3]
	v_lshl_add_u64 v[198:199], v[192:193], 0, s[2:3]
	s_cmp_gt_i32 s38, 0
	v_cndmask_b32_e64 v197, v199, v197, s[0:1]
	v_cndmask_b32_e64 v196, v198, v196, s[0:1]
	s_cselect_b32 s0, s13, 0x18000
	s_add_i32 s0, s35, s0
	s_add_i32 s39, s0, 0x4000
	s_mov_b32 m0, s0
	s_add_i32 s13, s0, 0x2000
	global_load_lds_dwordx4 v[196:197], off
	s_mov_b32 m0, s39
	s_add_i32 s1, s0, 0x6000
	v_lshl_add_u64 v[200:201], v[196:197], 0, s[72:73]
	global_load_lds_dwordx4 v[194:195], off
	s_mov_b32 m0, s13
	v_lshl_add_u64 v[198:199], v[194:195], 0, s[72:73]
	global_load_lds_dwordx4 v[200:201], off
	s_mov_b32 m0, s1
	s_nop 0
	global_load_lds_dwordx4 v[198:199], off
.LBB0_731:
	s_waitcnt lgkmcnt(0)
	v_mfma_f32_16x16x32_bf16 v[124:127], v[172:175], v[144:147], v[124:127]
	s_waitcnt lgkmcnt(0)
	v_mfma_f32_16x16x32_bf16 v[120:123], v[172:175], v[148:151], v[120:123]
	s_barrier
	v_mfma_f32_16x16x32_bf16 v[116:119], v[172:175], v[140:143], v[116:119]
	v_mfma_f32_16x16x32_bf16 v[112:115], v[172:175], v[132:135], v[112:115]
	v_mfma_f32_16x16x32_bf16 v[108:111], v[168:171], v[144:147], v[108:111]
	v_mfma_f32_16x16x32_bf16 v[104:107], v[168:171], v[148:151], v[104:107]
	v_mfma_f32_16x16x32_bf16 v[100:103], v[168:171], v[140:143], v[100:103]
	v_mfma_f32_16x16x32_bf16 v[96:99], v[168:171], v[132:135], v[96:99]
	v_mfma_f32_16x16x32_bf16 v[92:95], v[164:167], v[144:147], v[92:95]
	v_mfma_f32_16x16x32_bf16 v[88:91], v[164:167], v[148:151], v[88:91]
	v_mfma_f32_16x16x32_bf16 v[84:87], v[164:167], v[140:143], v[84:87]
	v_mfma_f32_16x16x32_bf16 v[80:83], v[164:167], v[132:135], v[80:83]
	v_mfma_f32_16x16x32_bf16 v[76:79], v[160:163], v[144:147], v[76:79]
	v_mfma_f32_16x16x32_bf16 v[72:75], v[160:163], v[148:151], v[72:75]
	v_mfma_f32_16x16x32_bf16 v[68:71], v[160:163], v[140:143], v[68:71]
	v_mfma_f32_16x16x32_bf16 v[64:67], v[160:163], v[132:135], v[64:67]
	v_mfma_f32_16x16x32_bf16 v[60:63], v[156:159], v[144:147], v[60:63]
	v_mfma_f32_16x16x32_bf16 v[56:59], v[156:159], v[148:151], v[56:59]
	v_mfma_f32_16x16x32_bf16 v[52:55], v[156:159], v[140:143], v[52:55]
	v_mfma_f32_16x16x32_bf16 v[48:51], v[156:159], v[132:135], v[48:51]
	v_mfma_f32_16x16x32_bf16 v[44:47], v[152:155], v[144:147], v[44:47]
	v_mfma_f32_16x16x32_bf16 v[40:43], v[152:155], v[148:151], v[40:43]
	v_mfma_f32_16x16x32_bf16 v[36:39], v[152:155], v[140:143], v[36:39]
	v_mfma_f32_16x16x32_bf16 v[32:35], v[152:155], v[132:135], v[32:35]
	v_mfma_f32_16x16x32_bf16 v[28:31], v[136:139], v[144:147], v[28:31]
	v_mfma_f32_16x16x32_bf16 v[24:27], v[136:139], v[148:151], v[24:27]
	v_mfma_f32_16x16x32_bf16 v[20:23], v[136:139], v[140:143], v[20:23]
	v_mfma_f32_16x16x32_bf16 v[16:19], v[136:139], v[132:135], v[16:19]
	v_mfma_f32_16x16x32_bf16 v[12:15], v[128:131], v[144:147], v[12:15]
	v_mfma_f32_16x16x32_bf16 v[8:11], v[128:131], v[148:151], v[8:11]
	v_mfma_f32_16x16x32_bf16 v[4:7], v[128:131], v[140:143], v[4:7]
	v_mfma_f32_16x16x32_bf16 v[0:3], v[128:131], v[132:135], v[0:3]
	s_cmp_lg_u64 s[8:9], 0
	s_cbranch_scc1 .Lgk_w4
	s_waitcnt vmcnt(8)
	s_branch .LBB0_728
